# v140 + phase-0 x->bf16/sum-of-squares loop software-pipelined (next row's 4 loads in flight, two register sets) instead of one load per vmcnt(0)
# speedup vs baseline: 1.0079x; 1.0059x over previous
.LBB0_54:
	s_or_b64 exec, exec, s[0:1]
	v_ashrrev_i32_e32 v87, 6, v22
	s_lshl_b32 s0, s24, 3
	v_writelane_b32 v253, s0, 4
	v_add_u32_e32 v0, s0, v87
	s_load_dword s0, s[60:61], 0x6c0
	v_and_b32_e32 v14, 63, v22
	v_mbcnt_lo_u32_b32 v52, -1, 0
	s_waitcnt lgkmcnt(0)
	s_lshl_b32 s28, s0, 3
	s_mov_b32 s0, 0x8000
	v_cmp_gt_i32_e32 vcc, s0, v0
	s_and_saveexec_b64 s[0:1], vcc
	s_cbranch_execz .LBB0_59
	v_mbcnt_hi_u32_b32 v1, -1, v52
	v_and_b32_e32 v2, 64, v1
	v_add_u32_e32 v2, 64, v2
	v_xor_b32_e32 v3, 1, v1
	v_cmp_lt_i32_e32 vcc, v3, v2
	s_load_dwordx2 s[10:11], s[60:61], 0x0
	s_mov_b64 s[2:3], 0x1f400000
	v_cndmask_b32_e32 v3, v1, v3, vcc
	v_lshlrev_b32_e32 v12, 2, v3
	v_xor_b32_e32 v3, 2, v1
	v_cmp_lt_i32_e32 vcc, v3, v2
	s_ashr_i32 s29, s28, 31
	v_cmp_gt_u32_e64 s[4:5], 4, v14
	v_cndmask_b32_e32 v3, v1, v3, vcc
	v_lshlrev_b32_e32 v13, 2, v3
	v_xor_b32_e32 v3, 4, v1
	v_cmp_lt_i32_e32 vcc, v3, v2
	v_cmp_eq_u32_e64 s[6:7], 0, v14
	s_lshl_b64 s[8:9], s[28:29], 11
	v_cndmask_b32_e32 v3, v1, v3, vcc
	v_lshlrev_b32_e32 v15, 2, v3
	v_xor_b32_e32 v3, 8, v1
	v_cmp_lt_i32_e32 vcc, v3, v2
	s_mov_b64 s[12:13], 0
	s_mov_b32 s16, 0x7000000
	v_cndmask_b32_e32 v3, v1, v3, vcc
	v_lshlrev_b32_e32 v16, 2, v3
	v_xor_b32_e32 v3, 16, v1
	v_cmp_lt_i32_e32 vcc, v3, v2
	s_movk_i32 s17, 0x7fff
	s_nop 0
	v_cndmask_b32_e32 v3, v1, v3, vcc
	v_lshlrev_b32_e32 v17, 2, v3
	v_xor_b32_e32 v3, 32, v1
	v_cmp_lt_i32_e32 vcc, v3, v2
	v_lshlrev_b32_e32 v2, 2, v14
	s_nop 0
	v_cndmask_b32_e32 v1, v1, v3, vcc
	v_lshlrev_b32_e32 v18, 2, v1
	v_ashrrev_i32_e32 v1, 31, v0
	v_lshlrev_b64 v[10:11], 12, v[0:1]
	v_mov_b32_e32 v3, 0
	v_lshl_or_b32 v10, v14, 4, v10
	v_lshl_add_u64 v[2:3], v[0:1], 4, v[2:3]
	v_lshlrev_b64 v[4:5], 11, v[0:1]
	s_waitcnt lgkmcnt(0)
	v_lshl_add_u64 v[10:11], s[10:11], 0, v[10:11]
	s_mov_b64 s[10:11], 0xc00
	v_lshl_add_u64 v[2:3], v[2:3], 0, s[2:3]
	s_lshl_b64 s[2:3], s[28:29], 4
	v_lshl_or_b32 v4, v14, 3, v4
	v_lshl_add_u64 v[10:11], v[10:11], 0, s[10:11]
	s_lshl_b64 s[10:11], s[28:29], 12
	v_mov_b32_e32 v1, v0
	global_load_dwordx4 v[24:27], v[10:11], off offset:-3072 nt
	global_load_dwordx4 v[28:31], v[10:11], off offset:-2048 nt
	global_load_dwordx4 v[32:35], v[10:11], off offset:-1024 nt
	global_load_dwordx4 v[36:39], v[10:11], off nt
.Lxb_loop:
	v_add_u32_e32 v1, s28, v1
	v_lshl_add_u64 v[10:11], v[10:11], 0, s[10:11]
	v_cmp_lt_i32_e32 vcc, s17, v1
	s_cbranch_vccnz .Lxb_tailA
	global_load_dwordx4 v[56:59], v[10:11], off offset:-3072 nt
	global_load_dwordx4 v[60:63], v[10:11], off offset:-2048 nt
	global_load_dwordx4 v[64:67], v[10:11], off offset:-1024 nt
	global_load_dwordx4 v[68:71], v[10:11], off nt
	s_waitcnt vmcnt(4)
	v_lshl_add_u64 v[20:21], v[6:7], 0, v[4:5]
	v_add_co_u32_e32 v40, vcc, s16, v20
	s_nop 0
	v_addc_co_u32_e32 v41, vcc, 0, v21, vcc
	v_mul_f32_e32 v19, v25, v25
	v_fmac_f32_e32 v19, v24, v24
	v_mul_f32_e32 v20, v27, v27
	v_fmac_f32_e32 v20, v26, v26
	v_add_f32_e32 v19, v19, v20
	v_mul_f32_e32 v20, v29, v29
	v_mul_f32_e32 v21, v31, v31
	v_fmac_f32_e32 v20, v28, v28
	v_fmac_f32_e32 v21, v30, v30
	v_add_f32_e32 v20, v20, v21
	v_add_f32_e32 v19, v19, v20
	v_mul_f32_e32 v20, v33, v33
	v_mul_f32_e32 v21, v35, v35
	v_fmac_f32_e32 v20, v32, v32
	v_fmac_f32_e32 v21, v34, v34
	v_add_f32_e32 v20, v20, v21
	v_add_f32_e32 v19, v19, v20
	v_mul_f32_e32 v20, v37, v37
	v_mul_f32_e32 v21, v39, v39
	v_fmac_f32_e32 v20, v36, v36
	v_fmac_f32_e32 v21, v38, v38
	v_add_f32_e32 v20, v20, v21
	v_add_f32_e32 v19, v19, v20
	ds_bpermute_b32 v20, v12, v19
	v_cvt_pk_bf16_f32 v24, v24, v25
	v_cvt_pk_bf16_f32 v25, v26, v27
	global_store_dwordx2 v[40:41], v[24:25], off
	v_cvt_pk_bf16_f32 v28, v28, v29
	v_cvt_pk_bf16_f32 v29, v30, v31
	global_store_dwordx2 v[40:41], v[28:29], off offset:512
	v_cvt_pk_bf16_f32 v32, v32, v33
	v_cvt_pk_bf16_f32 v33, v34, v35
	global_store_dwordx2 v[40:41], v[32:33], off offset:1024
	v_cvt_pk_bf16_f32 v36, v36, v37
	v_cvt_pk_bf16_f32 v37, v38, v39
	global_store_dwordx2 v[40:41], v[36:37], off offset:1536
	s_waitcnt lgkmcnt(0)
	v_add_f32_e32 v19, v19, v20
	ds_bpermute_b32 v20, v13, v19
	s_waitcnt lgkmcnt(0)
	v_add_f32_e32 v19, v19, v20
	ds_bpermute_b32 v20, v15, v19
	s_waitcnt lgkmcnt(0)
	v_add_f32_e32 v19, v19, v20
	ds_bpermute_b32 v20, v16, v19
	s_waitcnt lgkmcnt(0)
	v_add_f32_e32 v19, v19, v20
	ds_bpermute_b32 v20, v17, v19
	s_waitcnt lgkmcnt(0)
	v_add_f32_e32 v19, v19, v20
	ds_bpermute_b32 v20, v18, v19
	v_lshl_add_u64 v[4:5], v[4:5], 0, s[8:9]
	s_and_saveexec_b64 s[14:15], s[4:5]
	s_waitcnt lgkmcnt(0)
	v_add_f32_e32 v19, v19, v20
	v_lshl_add_u64 v[20:21], v[6:7], 0, v[2:3]
	v_cndmask_b32_e64 v19, 0, v19, s[6:7]
	s_nop 0
	global_store_dword v[20:21], v19, off
	s_or_b64 exec, exec, s[14:15]
	v_lshl_add_u64 v[2:3], v[2:3], 0, s[2:3]
	v_add_u32_e32 v1, s28, v1
	v_lshl_add_u64 v[10:11], v[10:11], 0, s[10:11]
	v_cmp_lt_i32_e32 vcc, s17, v1
	s_cbranch_vccnz .Lxb_tailB
	global_load_dwordx4 v[24:27], v[10:11], off offset:-3072 nt
	global_load_dwordx4 v[28:31], v[10:11], off offset:-2048 nt
	global_load_dwordx4 v[32:35], v[10:11], off offset:-1024 nt
	global_load_dwordx4 v[36:39], v[10:11], off nt
	s_waitcnt vmcnt(4)
	v_lshl_add_u64 v[20:21], v[6:7], 0, v[4:5]
	v_add_co_u32_e32 v40, vcc, s16, v20
	s_nop 0
	v_addc_co_u32_e32 v41, vcc, 0, v21, vcc
	v_mul_f32_e32 v19, v57, v57
	v_fmac_f32_e32 v19, v56, v56
	v_mul_f32_e32 v20, v59, v59
	v_fmac_f32_e32 v20, v58, v58
	v_add_f32_e32 v19, v19, v20
	v_mul_f32_e32 v20, v61, v61
	v_mul_f32_e32 v21, v63, v63
	v_fmac_f32_e32 v20, v60, v60
	v_fmac_f32_e32 v21, v62, v62
	v_add_f32_e32 v20, v20, v21
	v_add_f32_e32 v19, v19, v20
	v_mul_f32_e32 v20, v65, v65
	v_mul_f32_e32 v21, v67, v67
	v_fmac_f32_e32 v20, v64, v64
	v_fmac_f32_e32 v21, v66, v66
	v_add_f32_e32 v20, v20, v21
	v_add_f32_e32 v19, v19, v20
	v_mul_f32_e32 v20, v69, v69
	v_mul_f32_e32 v21, v71, v71
	v_fmac_f32_e32 v20, v68, v68
	v_fmac_f32_e32 v21, v70, v70
	v_add_f32_e32 v20, v20, v21
	v_add_f32_e32 v19, v19, v20
	ds_bpermute_b32 v20, v12, v19
	v_cvt_pk_bf16_f32 v56, v56, v57
	v_cvt_pk_bf16_f32 v57, v58, v59
	global_store_dwordx2 v[40:41], v[56:57], off
	v_cvt_pk_bf16_f32 v60, v60, v61
	v_cvt_pk_bf16_f32 v61, v62, v63
	global_store_dwordx2 v[40:41], v[60:61], off offset:512
	v_cvt_pk_bf16_f32 v64, v64, v65
	v_cvt_pk_bf16_f32 v65, v66, v67
	global_store_dwordx2 v[40:41], v[64:65], off offset:1024
	v_cvt_pk_bf16_f32 v68, v68, v69
	v_cvt_pk_bf16_f32 v69, v70, v71
	global_store_dwordx2 v[40:41], v[68:69], off offset:1536
	s_waitcnt lgkmcnt(0)
	v_add_f32_e32 v19, v19, v20
	ds_bpermute_b32 v20, v13, v19
	s_waitcnt lgkmcnt(0)
	v_add_f32_e32 v19, v19, v20
	ds_bpermute_b32 v20, v15, v19
	s_waitcnt lgkmcnt(0)
	v_add_f32_e32 v19, v19, v20
	ds_bpermute_b32 v20, v16, v19
	s_waitcnt lgkmcnt(0)
	v_add_f32_e32 v19, v19, v20
	ds_bpermute_b32 v20, v17, v19
	s_waitcnt lgkmcnt(0)
	v_add_f32_e32 v19, v19, v20
	ds_bpermute_b32 v20, v18, v19
	v_lshl_add_u64 v[4:5], v[4:5], 0, s[8:9]
	s_and_saveexec_b64 s[14:15], s[4:5]
	s_waitcnt lgkmcnt(0)
	v_add_f32_e32 v19, v19, v20
	v_lshl_add_u64 v[20:21], v[6:7], 0, v[2:3]
	v_cndmask_b32_e64 v19, 0, v19, s[6:7]
	s_nop 0
	global_store_dword v[20:21], v19, off
	s_or_b64 exec, exec, s[14:15]
	v_lshl_add_u64 v[2:3], v[2:3], 0, s[2:3]
	s_branch .Lxb_loop
.Lxb_tailA:
	s_waitcnt vmcnt(0)
	v_lshl_add_u64 v[20:21], v[6:7], 0, v[4:5]
	v_add_co_u32_e32 v40, vcc, s16, v20
	s_nop 0
	v_addc_co_u32_e32 v41, vcc, 0, v21, vcc
	v_mul_f32_e32 v19, v25, v25
	v_fmac_f32_e32 v19, v24, v24
	v_mul_f32_e32 v20, v27, v27
	v_fmac_f32_e32 v20, v26, v26
	v_add_f32_e32 v19, v19, v20
	v_mul_f32_e32 v20, v29, v29
	v_mul_f32_e32 v21, v31, v31
	v_fmac_f32_e32 v20, v28, v28
	v_fmac_f32_e32 v21, v30, v30
	v_add_f32_e32 v20, v20, v21
	v_add_f32_e32 v19, v19, v20
	v_mul_f32_e32 v20, v33, v33
	v_mul_f32_e32 v21, v35, v35
	v_fmac_f32_e32 v20, v32, v32
	v_fmac_f32_e32 v21, v34, v34
	v_add_f32_e32 v20, v20, v21
	v_add_f32_e32 v19, v19, v20
	v_mul_f32_e32 v20, v37, v37
	v_mul_f32_e32 v21, v39, v39
	v_fmac_f32_e32 v20, v36, v36
	v_fmac_f32_e32 v21, v38, v38
	v_add_f32_e32 v20, v20, v21
	v_add_f32_e32 v19, v19, v20
	ds_bpermute_b32 v20, v12, v19
	v_cvt_pk_bf16_f32 v24, v24, v25
	v_cvt_pk_bf16_f32 v25, v26, v27
	global_store_dwordx2 v[40:41], v[24:25], off
	v_cvt_pk_bf16_f32 v28, v28, v29
	v_cvt_pk_bf16_f32 v29, v30, v31
	global_store_dwordx2 v[40:41], v[28:29], off offset:512
	v_cvt_pk_bf16_f32 v32, v32, v33
	v_cvt_pk_bf16_f32 v33, v34, v35
	global_store_dwordx2 v[40:41], v[32:33], off offset:1024
	v_cvt_pk_bf16_f32 v36, v36, v37
	v_cvt_pk_bf16_f32 v37, v38, v39
	global_store_dwordx2 v[40:41], v[36:37], off offset:1536
	s_waitcnt lgkmcnt(0)
	v_add_f32_e32 v19, v19, v20
	ds_bpermute_b32 v20, v13, v19
	s_waitcnt lgkmcnt(0)
	v_add_f32_e32 v19, v19, v20
	ds_bpermute_b32 v20, v15, v19
	s_waitcnt lgkmcnt(0)
	v_add_f32_e32 v19, v19, v20
	ds_bpermute_b32 v20, v16, v19
	s_waitcnt lgkmcnt(0)
	v_add_f32_e32 v19, v19, v20
	ds_bpermute_b32 v20, v17, v19
	s_waitcnt lgkmcnt(0)
	v_add_f32_e32 v19, v19, v20
	ds_bpermute_b32 v20, v18, v19
	v_lshl_add_u64 v[4:5], v[4:5], 0, s[8:9]
	s_and_saveexec_b64 s[14:15], s[4:5]
	s_waitcnt lgkmcnt(0)
	v_add_f32_e32 v19, v19, v20
	v_lshl_add_u64 v[20:21], v[6:7], 0, v[2:3]
	v_cndmask_b32_e64 v19, 0, v19, s[6:7]
	s_nop 0
	global_store_dword v[20:21], v19, off
	s_or_b64 exec, exec, s[14:15]
	v_lshl_add_u64 v[2:3], v[2:3], 0, s[2:3]
	s_branch .Lxb_end
.Lxb_tailB:
	s_waitcnt vmcnt(0)
	v_lshl_add_u64 v[20:21], v[6:7], 0, v[4:5]
	v_add_co_u32_e32 v40, vcc, s16, v20
	s_nop 0
	v_addc_co_u32_e32 v41, vcc, 0, v21, vcc
	v_mul_f32_e32 v19, v57, v57
	v_fmac_f32_e32 v19, v56, v56
	v_mul_f32_e32 v20, v59, v59
	v_fmac_f32_e32 v20, v58, v58
	v_add_f32_e32 v19, v19, v20
	v_mul_f32_e32 v20, v61, v61
	v_mul_f32_e32 v21, v63, v63
	v_fmac_f32_e32 v20, v60, v60
	v_fmac_f32_e32 v21, v62, v62
	v_add_f32_e32 v20, v20, v21
	v_add_f32_e32 v19, v19, v20
	v_mul_f32_e32 v20, v65, v65
	v_mul_f32_e32 v21, v67, v67
	v_fmac_f32_e32 v20, v64, v64
	v_fmac_f32_e32 v21, v66, v66
	v_add_f32_e32 v20, v20, v21
	v_add_f32_e32 v19, v19, v20
	v_mul_f32_e32 v20, v69, v69
	v_mul_f32_e32 v21, v71, v71
	v_fmac_f32_e32 v20, v68, v68
	v_fmac_f32_e32 v21, v70, v70
	v_add_f32_e32 v20, v20, v21
	v_add_f32_e32 v19, v19, v20
	ds_bpermute_b32 v20, v12, v19
	v_cvt_pk_bf16_f32 v56, v56, v57
	v_cvt_pk_bf16_f32 v57, v58, v59
	global_store_dwordx2 v[40:41], v[56:57], off
	v_cvt_pk_bf16_f32 v60, v60, v61
	v_cvt_pk_bf16_f32 v61, v62, v63
	global_store_dwordx2 v[40:41], v[60:61], off offset:512
	v_cvt_pk_bf16_f32 v64, v64, v65
	v_cvt_pk_bf16_f32 v65, v66, v67
	global_store_dwordx2 v[40:41], v[64:65], off offset:1024
	v_cvt_pk_bf16_f32 v68, v68, v69
	v_cvt_pk_bf16_f32 v69, v70, v71
	global_store_dwordx2 v[40:41], v[68:69], off offset:1536
	s_waitcnt lgkmcnt(0)
	v_add_f32_e32 v19, v19, v20
	ds_bpermute_b32 v20, v13, v19
	s_waitcnt lgkmcnt(0)
	v_add_f32_e32 v19, v19, v20
	ds_bpermute_b32 v20, v15, v19
	s_waitcnt lgkmcnt(0)
	v_add_f32_e32 v19, v19, v20
	ds_bpermute_b32 v20, v16, v19
	s_waitcnt lgkmcnt(0)
	v_add_f32_e32 v19, v19, v20
	ds_bpermute_b32 v20, v17, v19
	s_waitcnt lgkmcnt(0)
	v_add_f32_e32 v19, v19, v20
	ds_bpermute_b32 v20, v18, v19
	v_lshl_add_u64 v[4:5], v[4:5], 0, s[8:9]
	s_and_saveexec_b64 s[14:15], s[4:5]
	s_waitcnt lgkmcnt(0)
	v_add_f32_e32 v19, v19, v20
	v_lshl_add_u64 v[20:21], v[6:7], 0, v[2:3]
	v_cndmask_b32_e64 v19, 0, v19, s[6:7]
	s_nop 0
	global_store_dword v[20:21], v19, off
	s_or_b64 exec, exec, s[14:15]
	v_lshl_add_u64 v[2:3], v[2:3], 0, s[2:3]
.Lxb_end:
.LBB0_59:
	s_or_b64 exec, exec, s[0:1]
	s_mov_b32 s3, s24
	s_load_dwordx2 s[38:39], s[60:61], 0x8
	s_load_dwordx2 s[40:41], s[60:61], 0x10
	s_load_dwordx2 s[42:43], s[60:61], 0x30
	s_load_dwordx2 s[44:45], s[60:61], 0x38
	s_load_dwordx2 s[48:49], s[60:61], 0x40
	s_load_dwordx2 s[50:51], s[60:61], 0x78
	s_load_dwordx2 s[52:53], s[60:61], 0x80
	s_load_dwordx2 s[54:55], s[60:61], 0x88
	s_load_dwordx2 s[56:57], s[60:61], 0xa0
	v_lshrrev_b32_e32 v8, 6, v175
	v_and_b32_e32 v9, 63, v175
	v_lshrrev_b32_e32 v1, 3, v9
	v_and_b32_e32 v2, 7, v9
	v_readfirstlane_b32 s20, v8
	v_lshlrev_b32_e32 v5, 5, v1
	v_lshlrev_b32_e32 v10, 14, v8
	v_mul_u32_u24_e32 v11, 33, v1
	v_lshl_add_u32 v11, v2, 2, v11
	v_lshl_add_u32 v3, v11, 2, v10
	v_mul_u32_u24_e32 v11, 264, v1
	v_add_u32_e32 v11, v11, v2
	v_lshl_add_u32 v4, v11, 2, v10
	v_mov_b32_e32 v16, 0
	v_mov_b32_e32 v17, 0
	v_mov_b32_e32 v18, 0
	v_mov_b32_e32 v19, 0
	v_lshl_add_u32 v12, s3, 9, v175
	v_lshlrev_b32_e32 v13, 4, v12
	s_movk_i32 s21, 0x6000
	v_cmp_gt_u32_e32 vcc, s21, v12
	s_and_saveexec_b64 s[22:23], vcc
	s_add_u32 s0, s36, 0x1820000
	s_addc_u32 s1, s37, 0
	global_store_dwordx4 v13, v[16:19], s[0:1]
	s_add_u32 s0, s0, 0x1080000
	s_addc_u32 s1, s1, 0
	global_store_dwordx4 v13, v[16:19], s[0:1]
	s_mov_b64 exec, s[22:23]
	s_lshl_b32 s2, s3, 3
	s_add_u32 s2, s2, s20
	s_waitcnt lgkmcnt(0)
	s_cmp_lt_u32 s2, 15040
	s_cselect_b32 s10, 1, 0
	s_cselect_b32 s20, s2, 0
	s_cmp_lt_u32 s20, 10816
	s_cbranch_scc0 .Lp0_ffn_1
	s_cmp_lt_u32 s20, 5408
	s_cselect_b32 s21, 0, 1
	s_cselect_b32 s22, 0, 5408
	s_sub_u32 s20, s20, s22
	s_cmp_lt_u32 s20, 768
	s_cbranch_scc1 .Lp0_k0_3
	s_sub_u32 s20, s20, 768
	s_cmp_lt_u32 s20, 512
	s_cbranch_scc1 .Lp0_k1_4
	s_sub_u32 s20, s20, 512
	s_cmp_lt_u32 s20, 3104
	s_cbranch_scc1 .Lp0_k2_5
	s_sub_u32 s20, s20, 3104
	s_branch .Lp0_k3_6
